# x28 + first QK MFMA of the dilated loop issued right after the K fragment reads, before the scalar tile search
# baseline (speedup 1.0000x reference)
.LBB0_69:
	s_waitcnt vmcnt(0)
	ds_read_b128 v[66:69], v241
	ds_read_b128 v[158:161], v241 offset:512
	ds_read_b128 v[170:173], v242
	ds_read_b128 v[162:165], v242 offset:512
	ds_read_b128 v[154:157], v241 offset:1024
	ds_read_b128 v[150:153], v241 offset:1536
	ds_read_b128 v[166:169], v242 offset:1024
	ds_read_b128 v[146:149], v242 offset:1536
	s_waitcnt lgkmcnt(0)
	v_mfma_f32_32x32x16_bf16 v[66:81], v[66:69], v[82:85], 0
	s_max_i32 s45, s29, 32
	s_lshl_b32 s10, s29, 5
	s_add_i32 s45, s45, 1
	s_add_i32 s43, s40, s10
	s_lshl_b32 s44, s29, 7
	s_branch .LBB0_72

.LBB0_87:
	ds_write_b128 v243, v[114:117]
	ds_write_b128 v244, v[118:121] offset:256
	ds_write_b128 v245, v[122:125] offset:2048
	ds_write_b128 v246, v[126:129] offset:2304
	ds_write_b128 v243, v[130:133] offset:4096
	ds_write_b128 v244, v[134:137] offset:4352
	ds_write_b128 v245, v[138:141] offset:6144
	ds_write_b128 v246, v[142:145] offset:6400
	v_mfma_f32_32x32x16_bf16 v[66:81], v[170:173], v[86:89], v[66:81]
	v_mov_b32_e32 v64, s43
	v_mad_u32_u24 v118, s44, v219, v64
	v_med3_i32 v64, v118, 0, v232
	v_mul_u32_u24_e32 v64, 0x3000, v64
	v_lshl_add_u64 v[114:115], s[22:23], 0, v[64:65]
	s_lshl_b32 s10, s44, 3
	v_lshl_add_u64 v[116:117], v[114:115], 0, v[188:189]
	v_add_u32_e32 v118, s10, v118
	s_mov_b32 m0, s16
	v_lshl_add_u64 v[116:117], v[116:117], 0, s[92:93]
	v_lshl_add_u64 v[114:115], v[114:115], 0, v[190:191]
	v_med3_i32 v64, v118, 0, v232
	global_load_lds_dwordx4 v[116:117], off
	v_lshl_add_u64 v[114:115], v[114:115], 0, s[92:93]
	s_mov_b32 m0, s30
	v_mul_u32_u24_e32 v64, 0x3000, v64
	global_load_lds_dwordx4 v[114:115], off
	v_mfma_f32_32x32x16_bf16 v[66:81], v[158:161], v[90:93], v[66:81]
	v_lshl_add_u64 v[114:115], s[22:23], 0, v[64:65]
	v_lshl_add_u64 v[116:117], v[192:193], 1, v[114:115]
	v_add_u32_e32 v118, s10, v118
	v_lshl_add_u64 v[116:117], v[116:117], 0, s[92:93]
	s_mov_b32 m0, s31
	v_lshl_add_u64 v[114:115], v[196:197], 1, v[114:115]
	v_med3_i32 v64, v118, 0, v232
	global_load_lds_dwordx4 v[116:117], off
	v_lshl_add_u64 v[114:115], v[114:115], 0, s[92:93]
	s_mov_b32 m0, s34
	v_mul_u32_u24_e32 v64, 0x3000, v64
	global_load_lds_dwordx4 v[114:115], off
	v_lshl_add_u64 v[114:115], s[22:23], 0, v[64:65]
	v_lshl_add_u64 v[116:117], v[114:115], 0, v[188:189]
	v_add_u32_e32 v64, s10, v118
	v_lshl_add_u64 v[116:117], v[116:117], 0, s[92:93]
	s_mov_b32 m0, s35
	v_mfma_f32_32x32x16_bf16 v[66:81], v[162:165], v[94:97], v[66:81]
	v_lshl_add_u64 v[114:115], v[114:115], 0, v[190:191]
	v_med3_i32 v64, v64, 0, v232
	global_load_lds_dwordx4 v[116:117], off
	v_lshl_add_u64 v[114:115], v[114:115], 0, s[92:93]
	s_mov_b32 m0, s2
	v_mul_u32_u24_e32 v64, 0x3000, v64
	global_load_lds_dwordx4 v[114:115], off
	v_lshl_add_u64 v[114:115], s[22:23], 0, v[64:65]
	v_lshl_add_u64 v[116:117], v[198:199], 1, v[114:115]
	v_lshl_add_u64 v[116:117], v[116:117], 0, s[92:93]
	s_mov_b32 m0, s36
	v_lshl_add_u64 v[114:115], v[200:201], 1, v[114:115]
	global_load_lds_dwordx4 v[116:117], off
	v_lshl_add_u64 v[114:115], v[114:115], 0, s[92:93]
	s_mov_b32 m0, s14
	global_load_lds_dwordx4 v[114:115], off
	s_mov_b64 s[10:11], 0
	v_mfma_f32_32x32x16_bf16 v[66:81], v[154:157], v[98:101], v[66:81]
	v_mul_lo_u32 v64, s44, v221
	v_add_u32_e32 v116, s43, v64
	v_med3_i32 v64, v116, 0, v232
	s_lshl_b32 s20, s44, 2
	v_mul_u32_u24_e32 v64, 0x3000, v64
	v_add_u32_e32 v122, s20, v116
	v_lshl_add_u64 v[114:115], v[202:203], 0, v[64:65]
	v_med3_i32 v64, v122, 0, v232
	v_mul_u32_u24_e32 v64, 0x3000, v64
	v_add_u32_e32 v124, s20, v122
	v_lshl_add_u64 v[118:119], v[202:203], 0, v[64:65]
	v_med3_i32 v64, v124, 0, v232
	v_mfma_f32_32x32x16_bf16 v[66:81], v[166:169], v[102:105], v[66:81]
	v_mul_u32_u24_e32 v64, 0x3000, v64
	v_add_u32_e32 v130, s20, v124
	v_lshl_add_u64 v[122:123], v[202:203], 0, v[64:65]
	v_med3_i32 v64, v130, 0, v232
	v_mul_u32_u24_e32 v64, 0x3000, v64
	v_add_u32_e32 v132, s20, v130
	v_lshl_add_u64 v[126:127], v[202:203], 0, v[64:65]
	v_med3_i32 v64, v132, 0, v232
	v_mul_u32_u24_e32 v64, 0x3000, v64
	v_add_u32_e32 v138, s20, v132
	v_lshl_add_u64 v[130:131], v[202:203], 0, v[64:65]
	v_med3_i32 v64, v138, 0, v232
	v_mfma_f32_32x32x16_bf16 v[66:81], v[150:153], v[106:109], v[66:81]
	v_mul_u32_u24_e32 v64, 0x3000, v64
	v_add_u32_e32 v140, s20, v138
	v_lshl_add_u64 v[134:135], v[202:203], 0, v[64:65]
	v_med3_i32 v64, v140, 0, v232
	v_mul_u32_u24_e32 v64, 0x3000, v64
	v_lshl_add_u64 v[138:139], v[202:203], 0, v[64:65]
	v_add_u32_e32 v64, s20, v140
	v_med3_i32 v64, v64, 0, v232
	v_mul_u32_u24_e32 v64, 0x3000, v64
	v_lshl_add_u64 v[142:143], v[202:203], 0, v[64:65]
	v_mfma_f32_32x32x16_bf16 v[66:81], v[146:149], v[110:113], v[66:81]
	global_load_dwordx4 v[114:117], v[114:115], off
	s_nop 0
	global_load_dwordx4 v[118:121], v[118:119], off
	s_nop 0
	global_load_dwordx4 v[122:125], v[122:123], off
	s_nop 0
	global_load_dwordx4 v[126:129], v[126:127], off
	s_nop 0
	global_load_dwordx4 v[130:133], v[130:131], off
	s_nop 0
	global_load_dwordx4 v[134:137], v[134:135], off
	s_nop 0
	global_load_dwordx4 v[138:141], v[138:139], off
	s_nop 0
	global_load_dwordx4 v[142:145], v[142:143], off
	s_branch .LBB0_90
.LBB0_88:
	s_xor_b64 s[10:11], s[20:21], -1
	ds_write_b128 v243, v[114:117]
	ds_write_b128 v244, v[118:121] offset:256
	ds_write_b128 v245, v[122:125] offset:2048
	ds_write_b128 v246, v[126:129] offset:2304
	ds_write_b128 v243, v[130:133] offset:4096
	ds_write_b128 v244, v[134:137] offset:4352
	ds_write_b128 v245, v[138:141] offset:6144
	ds_write_b128 v246, v[142:145] offset:6400
	v_mfma_f32_32x32x16_bf16 v[66:81], v[170:173], v[86:89], v[66:81]
	v_mfma_f32_32x32x16_bf16 v[66:81], v[158:161], v[90:93], v[66:81]
	v_mfma_f32_32x32x16_bf16 v[66:81], v[162:165], v[94:97], v[66:81]
	v_mfma_f32_32x32x16_bf16 v[66:81], v[154:157], v[98:101], v[66:81]
	v_mfma_f32_32x32x16_bf16 v[66:81], v[166:169], v[102:105], v[66:81]
	v_mfma_f32_32x32x16_bf16 v[66:81], v[150:153], v[106:109], v[66:81]
	v_mfma_f32_32x32x16_bf16 v[66:81], v[146:149], v[110:113], v[66:81]
	s_nop 3
